# A + first V reads/ones operand hoisted behind the last score MFMA (P4 T4)
# baseline (speedup 1.0000x reference)
.LBB0_3761:
	s_add_i32 s0, s51, 3
	s_sub_i32 s1, s0, s48
	s_min_u32 s2, s0, s1
	s_lshl_b64 s[0:1], s[2:3], 13
	s_waitcnt lgkmcnt(0)
	s_barrier
	s_waitcnt vmcnt(3)
	ds_write_b128 v199, v[124:127] offset:16384
	s_waitcnt vmcnt(2)
	ds_write_b128 v199, v[128:131] offset:24576
	v_lshl_add_u64 v[6:7], v[180:181], 0, s[0:1]
	v_lshl_add_u64 v[8:9], v[182:183], 0, s[0:1]
	global_load_dwordx4 v[124:127], v[6:7], off
	global_load_dwordx4 v[128:131], v[8:9], off
	s_cmp_gt_u32 s51, s47
	s_cbranch_scc1 .LBB0_3765
	ds_read_b128 v[6:9], v200
	ds_read_b128 v[10:13], v200 offset:512
	v_lshrrev_b32_e32 v1, v160, v152
	v_lshrrev_b32_e32 v14, v160, v153
	v_bitop3_b32 v228, v1, s27, v1 bitop3:0xc
	v_bitop3_b32 v229, v1, s28, v1 bitop3:0xc
	v_bitop3_b32 v230, v1, s29, v1 bitop3:0xc
	v_bitop3_b32 v231, v1, s30, v1 bitop3:0xc
	s_waitcnt lgkmcnt(1)
	v_mfma_f32_32x32x16_bf16 v[80:95], v[6:9], v[144:147], v[64:79]
	v_mul_u32_u24_e32 v228, 0xf000, v228
	v_mul_u32_u24_e32 v229, 0x7800, v229
	v_mul_u32_u24_e32 v230, 0x3c00, v230
	v_mul_u32_u24_e32 v231, 0x1e00, v231
	s_waitcnt lgkmcnt(0)
	v_mfma_f32_32x32x16_bf16 v[96:111], v[10:13], v[144:147], v[64:79]
	ds_read_b128 v[6:9], v200 offset:2048
	ds_read_b128 v[10:13], v200 offset:2560
	v_bitop3_b32 v232, v14, s27, v14 bitop3:0xc
	v_bitop3_b32 v233, v14, s28, v14 bitop3:0xc
	v_bitop3_b32 v234, v14, s29, v14 bitop3:0xc
	v_bitop3_b32 v235, v14, s30, v14 bitop3:0xc
	v_mul_u32_u24_e32 v232, 0xf000, v232
	v_mul_u32_u24_e32 v233, 0x7800, v233
	v_mul_u32_u24_e32 v234, 0x3c00, v234
	v_mul_u32_u24_e32 v235, 0x1e00, v235
	s_waitcnt lgkmcnt(1)
	v_mfma_f32_32x32x16_bf16 v[80:95], v[6:9], v[136:139], v[80:95]
	v_bitop3_b32 v236, v1, s31, v1 bitop3:0xc
	v_bitop3_b32 v237, v1, s33, v1 bitop3:0xc
	v_bitop3_b32 v238, v1, s34, v1 bitop3:0xc
	v_bitop3_b32 v239, v1, s35, v1 bitop3:0xc
	s_waitcnt lgkmcnt(0)
	v_mfma_f32_32x32x16_bf16 v[96:111], v[10:13], v[136:139], v[96:111]
	ds_read_b128 v[6:9], v200 offset:4096
	ds_read_b128 v[10:13], v200 offset:4608
	v_mul_u32_u24_e32 v236, 0xf00, v236
	v_mul_u32_u24_e32 v237, 0x780, v237
	v_mul_u32_u24_e32 v238, 0x3c0, v238
	v_mul_u32_u24_e32 v239, 0x1e0, v239
	v_bitop3_b32 v224, v14, s31, v14 bitop3:0xc
	v_bitop3_b32 v225, v14, s33, v14 bitop3:0xc
	v_bitop3_b32 v226, v14, s34, v14 bitop3:0xc
	v_bitop3_b32 v227, v14, s35, v14 bitop3:0xc
	s_waitcnt lgkmcnt(1)
	v_mfma_f32_32x32x16_bf16 v[80:95], v[6:9], v[140:143], v[80:95]
	v_mul_u32_u24_e32 v224, 0xf00, v224
	v_mul_u32_u24_e32 v225, 0x780, v225
	v_mul_u32_u24_e32 v226, 0x3c0, v226
	v_mul_u32_u24_e32 v227, 0x1e0, v227
	s_waitcnt lgkmcnt(0)
	v_mfma_f32_32x32x16_bf16 v[96:111], v[10:13], v[140:143], v[96:111]
	ds_read_b128 v[6:9], v200 offset:6144
	ds_read_b128 v[10:13], v200 offset:6656
	s_xor_b64 s[4:5], s[20:21], -1
	s_waitcnt lgkmcnt(1)
	v_mfma_f32_32x32x16_bf16 v[80:95], v[6:9], v[148:151], v[80:95]
	s_waitcnt lgkmcnt(0)
	v_mfma_f32_32x32x16_bf16 v[96:111], v[10:13], v[148:151], v[96:111]
	v_mfma_f32_32x32x16_bf16 v[80:95], v[112:115], v[228:231], v[80:95]
	v_mfma_f32_32x32x16_bf16 v[96:111], v[112:115], v[232:235], v[96:111]
	v_mfma_f32_32x32x16_bf16 v[80:95], v[116:119], v[236:239], v[80:95]
	v_mfma_f32_32x32x16_bf16 v[96:111], v[116:119], v[224:227], v[96:111]
	v_add_u32_e32 v218, 0, v157
	ds_read_b64_tr_b16 v[202:203], v218 offset:8192
	ds_read_b64_tr_b16 v[204:205], v218 offset:8704
	ds_read_b64_tr_b16 v[206:207], v218 offset:12288
	ds_read_b64_tr_b16 v[208:209], v218 offset:12800
	s_mov_b32 s9, s8
	v_mov_b64_e32 v[224:225], s[8:9]
	v_mov_b64_e32 v[226:227], s[8:9]
	s_nop 15
	v_max3_f32 v1, v80, v81, v82
	v_max3_f32 v6, v83, v84, v85
	v_max3_f32 v1, v1, v86, v87
	v_max3_f32 v6, v6, v88, v89
	v_max3_f32 v1, v1, v90, v91
	v_max3_f32 v6, v6, v92, v93
	v_max3_f32 v1, v1, v94, v95
	v_max_f32 v1, v1, v6
	s_nop 0
	v_max3_f32 v7, v96, v97, v98
	v_max3_f32 v6, v99, v100, v101
	v_max3_f32 v7, v7, v102, v103
	v_max3_f32 v6, v6, v104, v105
	v_max3_f32 v7, v7, v106, v107
	v_max3_f32 v6, v6, v108, v109
	v_max3_f32 v7, v7, v110, v111
	v_max3_f32 v7, v7, v6, v1
	s_nop 0
	v_mov_b32_e32 v1, v7
	s_nop 1
	v_permlane32_swap_b32_e32 v7, v1
	v_max_f32_e32 v1, v1, v1
	v_max_f32_e32 v6, v7, v7
	v_max_f32_e32 v1, v6, v1
	v_cmp_lt_f32_e64 s[0:1], s36, v1
	s_and_b64 s[10:11], s[0:1], s[4:5]
	v_cmp_lt_f32_e32 vcc, s37, v1
	s_or_b64 s[4:5], vcc, s[10:11]
	v_cndmask_b32_e64 v6, 0, 1, s[4:5]
	v_cmp_ne_u32_e32 vcc, 0, v6
	s_cbranch_vccz .LBB0_3764
	v_cndmask_b32_e64 v6, 0, v1, s[4:5]
	v_exp_f32_e64 v1, -v6
	v_add_f32_e32 v171, v171, v6
	s_or_b64 s[0:1], s[20:21], s[0:1]
	v_xor_b32_e32 v64, 0x80000000, v171
	v_cndmask_b32_e64 v8, v1, 1.0, s[10:11]
	s_andn2_b64 s[4:5], s[20:21], exec
	s_and_b64 s[0:1], s[0:1], exec
	v_pk_add_f32 v[80:81], v[80:81], v[6:7] op_sel_hi:[1,0] neg_lo:[0,1] neg_hi:[0,1]
	v_pk_add_f32 v[96:97], v[96:97], v[6:7] op_sel_hi:[1,0] neg_lo:[0,1] neg_hi:[0,1]
	v_pk_add_f32 v[82:83], v[82:83], v[6:7] op_sel_hi:[1,0] neg_lo:[0,1] neg_hi:[0,1]
	v_pk_add_f32 v[98:99], v[98:99], v[6:7] op_sel_hi:[1,0] neg_lo:[0,1] neg_hi:[0,1]
	v_pk_add_f32 v[84:85], v[84:85], v[6:7] op_sel_hi:[1,0] neg_lo:[0,1] neg_hi:[0,1]
	v_pk_add_f32 v[100:101], v[100:101], v[6:7] op_sel_hi:[1,0] neg_lo:[0,1] neg_hi:[0,1]
	v_pk_add_f32 v[86:87], v[86:87], v[6:7] op_sel_hi:[1,0] neg_lo:[0,1] neg_hi:[0,1]
	v_pk_add_f32 v[102:103], v[102:103], v[6:7] op_sel_hi:[1,0] neg_lo:[0,1] neg_hi:[0,1]
	v_pk_add_f32 v[88:89], v[88:89], v[6:7] op_sel_hi:[1,0] neg_lo:[0,1] neg_hi:[0,1]
	v_pk_add_f32 v[104:105], v[104:105], v[6:7] op_sel_hi:[1,0] neg_lo:[0,1] neg_hi:[0,1]
	v_pk_add_f32 v[90:91], v[90:91], v[6:7] op_sel_hi:[1,0] neg_lo:[0,1] neg_hi:[0,1]
	v_pk_add_f32 v[106:107], v[106:107], v[6:7] op_sel_hi:[1,0] neg_lo:[0,1] neg_hi:[0,1]
	v_pk_add_f32 v[92:93], v[92:93], v[6:7] op_sel_hi:[1,0] neg_lo:[0,1] neg_hi:[0,1]
	v_pk_add_f32 v[108:109], v[108:109], v[6:7] op_sel_hi:[1,0] neg_lo:[0,1] neg_hi:[0,1]
	v_pk_add_f32 v[94:95], v[94:95], v[6:7] op_sel_hi:[1,0] neg_lo:[0,1] neg_hi:[0,1]
	v_pk_add_f32 v[110:111], v[110:111], v[6:7] op_sel_hi:[1,0] neg_lo:[0,1] neg_hi:[0,1]
	v_mov_b32_e32 v65, v64
	v_mov_b32_e32 v66, v64
	v_mov_b32_e32 v67, v64
	v_mov_b32_e32 v68, v64
	v_mov_b32_e32 v69, v64
	v_mov_b32_e32 v70, v64
	v_mov_b32_e32 v71, v64
	v_mov_b32_e32 v72, v64
	v_mov_b32_e32 v73, v64
	v_mov_b32_e32 v74, v64
	v_mov_b32_e32 v75, v64
	v_mov_b32_e32 v76, v64
	v_mov_b32_e32 v77, v64
	v_mov_b32_e32 v78, v64
	v_mov_b32_e32 v79, v64
	v_pk_mul_f32 v[30:31], v[30:31], v[8:9] op_sel_hi:[1,0]
	v_pk_mul_f32 v[28:29], v[28:29], v[8:9] op_sel_hi:[1,0]
	v_pk_mul_f32 v[26:27], v[26:27], v[8:9] op_sel_hi:[1,0]
	v_pk_mul_f32 v[24:25], v[24:25], v[8:9] op_sel_hi:[1,0]
	v_pk_mul_f32 v[22:23], v[22:23], v[8:9] op_sel_hi:[1,0]
	v_pk_mul_f32 v[20:21], v[20:21], v[8:9] op_sel_hi:[1,0]
	v_pk_mul_f32 v[18:19], v[18:19], v[8:9] op_sel_hi:[1,0]
	v_pk_mul_f32 v[16:17], v[16:17], v[8:9] op_sel_hi:[1,0]
	v_pk_mul_f32 v[46:47], v[46:47], v[8:9] op_sel_hi:[1,0]
	v_pk_mul_f32 v[44:45], v[44:45], v[8:9] op_sel_hi:[1,0]
	v_pk_mul_f32 v[42:43], v[42:43], v[8:9] op_sel_hi:[1,0]
	v_pk_mul_f32 v[40:41], v[40:41], v[8:9] op_sel_hi:[1,0]
	v_pk_mul_f32 v[38:39], v[38:39], v[8:9] op_sel_hi:[1,0]
	v_pk_mul_f32 v[36:37], v[36:37], v[8:9] op_sel_hi:[1,0]
	v_pk_mul_f32 v[34:35], v[34:35], v[8:9] op_sel_hi:[1,0]
	v_pk_mul_f32 v[32:33], v[32:33], v[8:9] op_sel_hi:[1,0]
	v_pk_mul_f32 v[62:63], v[62:63], v[8:9] op_sel_hi:[1,0]
	v_pk_mul_f32 v[60:61], v[60:61], v[8:9] op_sel_hi:[1,0]
	v_pk_mul_f32 v[58:59], v[58:59], v[8:9] op_sel_hi:[1,0]
	v_pk_mul_f32 v[56:57], v[56:57], v[8:9] op_sel_hi:[1,0]
	v_pk_mul_f32 v[54:55], v[54:55], v[8:9] op_sel_hi:[1,0]
	v_pk_mul_f32 v[52:53], v[52:53], v[8:9] op_sel_hi:[1,0]
	v_pk_mul_f32 v[50:51], v[50:51], v[8:9] op_sel_hi:[1,0]
	v_pk_mul_f32 v[48:49], v[48:49], v[8:9] op_sel_hi:[1,0]
	s_or_b64 s[20:21], s[4:5], s[0:1]
.LBB0_3764:
	v_exp_f32_e32 v80, v80
	v_exp_f32_e32 v81, v81
	v_exp_f32_e32 v82, v82
	v_exp_f32_e32 v83, v83
	v_exp_f32_e32 v84, v84
	v_exp_f32_e32 v85, v85
	v_exp_f32_e32 v86, v86
	v_exp_f32_e32 v87, v87
	v_cvt_pk_bf16_f32 v6, v80, v81
	v_cvt_pk_bf16_f32 v7, v82, v83
	v_cvt_pk_bf16_f32 v8, v84, v85
	v_cvt_pk_bf16_f32 v9, v86, v87
	ds_read_b64_tr_b16 v[210:211], v218 offset:9216
	ds_read_b64_tr_b16 v[212:213], v218 offset:9728
	ds_read_b64_tr_b16 v[214:215], v218 offset:13312
	ds_read_b64_tr_b16 v[216:217], v218 offset:13824
	s_waitcnt lgkmcnt(4)
	v_mfma_f32_32x32x16_bf16 v[16:31], v[202:205], v[6:9], v[16:31]
	v_exp_f32_e32 v88, v88
	v_exp_f32_e32 v89, v89
	v_exp_f32_e32 v90, v90
	v_mfma_f32_32x32x16_bf16 v[32:47], v[206:209], v[6:9], v[32:47]
	v_exp_f32_e32 v91, v91
	v_exp_f32_e32 v92, v92
	v_exp_f32_e32 v93, v93
	v_mfma_f32_32x32x16_bf16 v[48:63], v[224:227], v[6:9], v[48:63]
	v_exp_f32_e32 v94, v94
	v_exp_f32_e32 v95, v95
	v_cvt_pk_bf16_f32 v10, v88, v89
	v_cvt_pk_bf16_f32 v11, v90, v91
	v_cvt_pk_bf16_f32 v12, v92, v93
	v_cvt_pk_bf16_f32 v13, v94, v95
	ds_read_b64_tr_b16 v[202:203], v218 offset:10240
	ds_read_b64_tr_b16 v[204:205], v218 offset:10752
	ds_read_b64_tr_b16 v[206:207], v218 offset:14336
	ds_read_b64_tr_b16 v[208:209], v218 offset:14848
	s_waitcnt lgkmcnt(4)
	v_mfma_f32_32x32x16_bf16 v[16:31], v[210:213], v[10:13], v[16:31]
	v_exp_f32_e32 v96, v96
	v_exp_f32_e32 v97, v97
	v_exp_f32_e32 v98, v98
	v_mfma_f32_32x32x16_bf16 v[32:47], v[214:217], v[10:13], v[32:47]
	v_exp_f32_e32 v99, v99
	v_exp_f32_e32 v100, v100
	v_exp_f32_e32 v101, v101
	v_mfma_f32_32x32x16_bf16 v[48:63], v[224:227], v[10:13], v[48:63]
	v_exp_f32_e32 v102, v102
	v_exp_f32_e32 v103, v103
	v_cvt_pk_bf16_f32 v228, v96, v97
	v_cvt_pk_bf16_f32 v229, v98, v99
	v_cvt_pk_bf16_f32 v230, v100, v101
	v_cvt_pk_bf16_f32 v231, v102, v103
	ds_read_b64_tr_b16 v[210:211], v218 offset:11264
	ds_read_b64_tr_b16 v[212:213], v218 offset:11776
	ds_read_b64_tr_b16 v[214:215], v218 offset:15360
	ds_read_b64_tr_b16 v[216:217], v218 offset:15872
	s_waitcnt lgkmcnt(4)
	v_mfma_f32_32x32x16_bf16 v[16:31], v[202:205], v[228:231], v[16:31]
	v_exp_f32_e32 v104, v104
	v_exp_f32_e32 v105, v105
	v_exp_f32_e32 v106, v106
	v_mfma_f32_32x32x16_bf16 v[32:47], v[206:209], v[228:231], v[32:47]
	v_exp_f32_e32 v107, v107
	v_exp_f32_e32 v108, v108
	v_exp_f32_e32 v109, v109
	v_mfma_f32_32x32x16_bf16 v[48:63], v[224:227], v[228:231], v[48:63]
	v_exp_f32_e32 v110, v110
	v_exp_f32_e32 v111, v111
	v_cvt_pk_bf16_f32 v232, v104, v105
	v_cvt_pk_bf16_f32 v233, v106, v107
	v_cvt_pk_bf16_f32 v234, v108, v109
	v_cvt_pk_bf16_f32 v235, v110, v111
	s_waitcnt lgkmcnt(0)
	s_nop 0
	v_mfma_f32_32x32x16_bf16 v[16:31], v[210:213], v[232:235], v[16:31]
	v_mfma_f32_32x32x16_bf16 v[32:47], v[214:217], v[232:235], v[32:47]
	v_mfma_f32_32x32x16_bf16 v[48:63], v[224:227], v[232:235], v[48:63]
.LBB0_3765:
	s_cmp_ge_u32 s51, s46
	s_cselect_b32 s0, s49, 4
	s_add_i32 s0, s0, s51
	s_ashr_i32 s1, s0, 31
	s_lshl_b64 s[0:1], s[0:1], 13
	s_waitcnt lgkmcnt(0)
	s_barrier
	s_waitcnt vmcnt(3)
	ds_write_b128 v199, v[120:123]
	s_waitcnt vmcnt(2)
	ds_write_b128 v199, v[132:135] offset:8192
	v_lshl_add_u64 v[6:7], v[180:181], 0, s[0:1]
	v_lshl_add_u64 v[8:9], v[182:183], 0, s[0:1]
	global_load_dwordx4 v[120:123], v[6:7], off
	global_load_dwordx4 v[132:135], v[8:9], off
	s_cmp_ge_u32 s51, s47
	s_cbranch_scc1 .LBB0_3770
	ds_read_b128 v[6:9], v200 offset:16384
	ds_read_b128 v[10:13], v200 offset:16896
	v_lshrrev_b32_e32 v1, v160, v154
	v_lshrrev_b32_e32 v14, v160, v155
	v_bitop3_b32 v228, v1, s27, v1 bitop3:0xc
	v_bitop3_b32 v229, v1, s28, v1 bitop3:0xc
	v_bitop3_b32 v230, v1, s29, v1 bitop3:0xc
	v_bitop3_b32 v231, v1, s30, v1 bitop3:0xc
	s_waitcnt lgkmcnt(1)
	v_mfma_f32_32x32x16_bf16 v[80:95], v[6:9], v[144:147], v[64:79]
	v_mul_u32_u24_e32 v228, 0xf000, v228
	v_mul_u32_u24_e32 v229, 0x7800, v229
	v_mul_u32_u24_e32 v230, 0x3c00, v230
	v_mul_u32_u24_e32 v231, 0x1e00, v231
	s_waitcnt lgkmcnt(0)
	v_mfma_f32_32x32x16_bf16 v[96:111], v[10:13], v[144:147], v[64:79]
	ds_read_b128 v[6:9], v200 offset:18432
	ds_read_b128 v[10:13], v200 offset:18944
	v_bitop3_b32 v232, v14, s27, v14 bitop3:0xc
	v_bitop3_b32 v233, v14, s28, v14 bitop3:0xc
	v_bitop3_b32 v234, v14, s29, v14 bitop3:0xc
	v_bitop3_b32 v235, v14, s30, v14 bitop3:0xc
	v_mul_u32_u24_e32 v232, 0xf000, v232
	v_mul_u32_u24_e32 v233, 0x7800, v233
	v_mul_u32_u24_e32 v234, 0x3c00, v234
	v_mul_u32_u24_e32 v235, 0x1e00, v235
	s_waitcnt lgkmcnt(1)
	v_mfma_f32_32x32x16_bf16 v[80:95], v[6:9], v[136:139], v[80:95]
	v_bitop3_b32 v236, v1, s31, v1 bitop3:0xc
	v_bitop3_b32 v237, v1, s33, v1 bitop3:0xc
	v_bitop3_b32 v238, v1, s34, v1 bitop3:0xc
	v_bitop3_b32 v239, v1, s35, v1 bitop3:0xc
	s_waitcnt lgkmcnt(0)
	v_mfma_f32_32x32x16_bf16 v[96:111], v[10:13], v[136:139], v[96:111]
	ds_read_b128 v[6:9], v200 offset:20480
	ds_read_b128 v[10:13], v200 offset:20992
	v_mul_u32_u24_e32 v236, 0xf00, v236
	v_mul_u32_u24_e32 v237, 0x780, v237
	v_mul_u32_u24_e32 v238, 0x3c0, v238
	v_mul_u32_u24_e32 v239, 0x1e0, v239
	v_bitop3_b32 v224, v14, s31, v14 bitop3:0xc
	v_bitop3_b32 v225, v14, s33, v14 bitop3:0xc
	v_bitop3_b32 v226, v14, s34, v14 bitop3:0xc
	v_bitop3_b32 v227, v14, s35, v14 bitop3:0xc
	s_waitcnt lgkmcnt(1)
	v_mfma_f32_32x32x16_bf16 v[80:95], v[6:9], v[140:143], v[80:95]
	v_mul_u32_u24_e32 v224, 0xf00, v224
	v_mul_u32_u24_e32 v225, 0x780, v225
	v_mul_u32_u24_e32 v226, 0x3c0, v226
	v_mul_u32_u24_e32 v227, 0x1e0, v227
	s_waitcnt lgkmcnt(0)
	v_mfma_f32_32x32x16_bf16 v[96:111], v[10:13], v[140:143], v[96:111]
	ds_read_b128 v[6:9], v200 offset:22528
	ds_read_b128 v[10:13], v200 offset:23040
	s_xor_b64 s[4:5], s[20:21], -1
	v_cndmask_b32_e64 v1, 0, 1, s[4:5]
	v_cmp_ne_u32_e32 vcc, 0, v1
	s_waitcnt lgkmcnt(1)
	v_mfma_f32_32x32x16_bf16 v[80:95], v[6:9], v[148:151], v[80:95]
	s_waitcnt lgkmcnt(0)
	v_mfma_f32_32x32x16_bf16 v[96:111], v[10:13], v[148:151], v[96:111]
	v_mfma_f32_32x32x16_bf16 v[80:95], v[112:115], v[228:231], v[80:95]
	v_mfma_f32_32x32x16_bf16 v[96:111], v[112:115], v[232:235], v[96:111]
	v_mfma_f32_32x32x16_bf16 v[80:95], v[116:119], v[236:239], v[80:95]
	v_mfma_f32_32x32x16_bf16 v[96:111], v[116:119], v[224:227], v[96:111]
	v_add_u32_e32 v218, 0, v157
	ds_read_b64_tr_b16 v[202:203], v218 offset:24576
	ds_read_b64_tr_b16 v[204:205], v218 offset:25088
	ds_read_b64_tr_b16 v[206:207], v218 offset:28672
	ds_read_b64_tr_b16 v[208:209], v218 offset:29184
	s_mov_b32 s9, s8
	v_mov_b64_e32 v[224:225], s[8:9]
	v_mov_b64_e32 v[226:227], s[8:9]
	s_cbranch_vccz .LBB0_3769
	s_nop 15
	s_nop 7
	v_max3_f32 v1, v80, v81, v82
	v_max3_f32 v6, v83, v84, v85
	v_max3_f32 v1, v1, v86, v87
	v_max3_f32 v6, v6, v88, v89
	v_max3_f32 v1, v1, v90, v91
	v_max3_f32 v6, v6, v92, v93
	v_max3_f32 v1, v1, v94, v95
	v_max_f32 v1, v1, v6
	s_nop 0
	v_max3_f32 v7, v96, v97, v98
	v_max3_f32 v6, v99, v100, v101
	v_max3_f32 v7, v7, v102, v103
	v_max3_f32 v6, v6, v104, v105
	v_max3_f32 v7, v7, v106, v107
	v_max3_f32 v6, v6, v108, v109
	v_max3_f32 v7, v7, v110, v111
	v_max3_f32 v7, v7, v6, v1
	s_nop 0
	v_mov_b32_e32 v1, v7
	s_nop 1
	v_permlane32_swap_b32_e32 v7, v1
	v_max_f32_e32 v1, v1, v1
	v_max_f32_e32 v6, v7, v7
	v_max_f32_e32 v1, v6, v1
	v_cmp_lt_f32_e64 s[0:1], s36, v1
	s_and_b64 s[10:11], s[0:1], s[4:5]
	v_cmp_lt_f32_e32 vcc, s37, v1
	s_or_b64 s[4:5], vcc, s[10:11]
	v_cndmask_b32_e64 v6, 0, 1, s[4:5]
	v_cmp_ne_u32_e32 vcc, 0, v6
	s_cbranch_vccz .LBB0_3769
	v_cndmask_b32_e64 v1, 0, v1, s[4:5]
	v_exp_f32_e64 v6, -v1
	v_add_f32_e32 v171, v171, v1
	s_or_b64 s[0:1], s[20:21], s[0:1]
	v_xor_b32_e32 v64, 0x80000000, v171
	v_cndmask_b32_e64 v6, v6, 1.0, s[10:11]
	s_andn2_b64 s[4:5], s[20:21], exec
	s_and_b64 s[0:1], s[0:1], exec
	v_mov_b32_e32 v65, v64
	v_mov_b32_e32 v66, v64
	v_mov_b32_e32 v67, v64
	v_mov_b32_e32 v68, v64
	v_mov_b32_e32 v69, v64
	v_mov_b32_e32 v70, v64
	v_mov_b32_e32 v71, v64
	v_mov_b32_e32 v72, v64
	v_mov_b32_e32 v73, v64
	v_mov_b32_e32 v74, v64
	v_mov_b32_e32 v75, v64
	v_mov_b32_e32 v76, v64
	v_mov_b32_e32 v77, v64
	v_mov_b32_e32 v78, v64
	v_mov_b32_e32 v79, v64
	v_pk_mul_f32 v[30:31], v[30:31], v[6:7] op_sel_hi:[1,0]
	v_pk_mul_f32 v[28:29], v[28:29], v[6:7] op_sel_hi:[1,0]
	v_pk_mul_f32 v[26:27], v[26:27], v[6:7] op_sel_hi:[1,0]
	v_pk_mul_f32 v[24:25], v[24:25], v[6:7] op_sel_hi:[1,0]
	v_pk_mul_f32 v[22:23], v[22:23], v[6:7] op_sel_hi:[1,0]
	v_pk_mul_f32 v[20:21], v[20:21], v[6:7] op_sel_hi:[1,0]
	v_pk_mul_f32 v[18:19], v[18:19], v[6:7] op_sel_hi:[1,0]
	v_pk_mul_f32 v[16:17], v[16:17], v[6:7] op_sel_hi:[1,0]
	v_pk_mul_f32 v[46:47], v[46:47], v[6:7] op_sel_hi:[1,0]
	v_pk_mul_f32 v[44:45], v[44:45], v[6:7] op_sel_hi:[1,0]
	v_pk_mul_f32 v[42:43], v[42:43], v[6:7] op_sel_hi:[1,0]
	v_pk_mul_f32 v[40:41], v[40:41], v[6:7] op_sel_hi:[1,0]
	v_pk_mul_f32 v[38:39], v[38:39], v[6:7] op_sel_hi:[1,0]
	v_pk_mul_f32 v[36:37], v[36:37], v[6:7] op_sel_hi:[1,0]
	v_pk_mul_f32 v[34:35], v[34:35], v[6:7] op_sel_hi:[1,0]
	v_pk_mul_f32 v[32:33], v[32:33], v[6:7] op_sel_hi:[1,0]
	v_pk_mul_f32 v[62:63], v[62:63], v[6:7] op_sel_hi:[1,0]
	v_pk_mul_f32 v[60:61], v[60:61], v[6:7] op_sel_hi:[1,0]
	v_pk_mul_f32 v[58:59], v[58:59], v[6:7] op_sel_hi:[1,0]
	v_pk_mul_f32 v[56:57], v[56:57], v[6:7] op_sel_hi:[1,0]
	v_pk_mul_f32 v[54:55], v[54:55], v[6:7] op_sel_hi:[1,0]
	v_pk_mul_f32 v[52:53], v[52:53], v[6:7] op_sel_hi:[1,0]
	v_pk_mul_f32 v[50:51], v[50:51], v[6:7] op_sel_hi:[1,0]
	v_pk_mul_f32 v[48:49], v[48:49], v[6:7] op_sel_hi:[1,0]
	v_sub_f32_e32 v95, v95, v1
	v_sub_f32_e32 v94, v94, v1
	v_sub_f32_e32 v93, v93, v1
	v_sub_f32_e32 v92, v92, v1
	v_sub_f32_e32 v91, v91, v1
	v_sub_f32_e32 v90, v90, v1
	v_sub_f32_e32 v89, v89, v1
	v_sub_f32_e32 v88, v88, v1
	v_sub_f32_e32 v87, v87, v1
	v_sub_f32_e32 v86, v86, v1
	v_sub_f32_e32 v85, v85, v1
	v_sub_f32_e32 v84, v84, v1
	v_sub_f32_e32 v83, v83, v1
	v_sub_f32_e32 v82, v82, v1
	v_sub_f32_e32 v81, v81, v1
	v_sub_f32_e32 v80, v80, v1
	v_sub_f32_e32 v111, v111, v1
	v_sub_f32_e32 v110, v110, v1
	v_sub_f32_e32 v109, v109, v1
	v_sub_f32_e32 v108, v108, v1
	v_sub_f32_e32 v107, v107, v1
	v_sub_f32_e32 v106, v106, v1
	v_sub_f32_e32 v105, v105, v1
	v_sub_f32_e32 v104, v104, v1
	v_sub_f32_e32 v103, v103, v1
	v_sub_f32_e32 v102, v102, v1
	v_sub_f32_e32 v101, v101, v1
	v_sub_f32_e32 v100, v100, v1
	v_sub_f32_e32 v99, v99, v1
	v_sub_f32_e32 v98, v98, v1
	v_sub_f32_e32 v97, v97, v1
	v_sub_f32_e32 v96, v96, v1
	s_or_b64 s[20:21], s[4:5], s[0:1]
.LBB0_3769:
	s_nop 8
	v_exp_f32_e32 v80, v80
	v_exp_f32_e32 v81, v81
	v_exp_f32_e32 v82, v82
	v_exp_f32_e32 v83, v83
	v_exp_f32_e32 v84, v84
	v_exp_f32_e32 v85, v85
	v_exp_f32_e32 v86, v86
	v_exp_f32_e32 v87, v87
	v_cvt_pk_bf16_f32 v6, v80, v81
	v_cvt_pk_bf16_f32 v7, v82, v83
	v_cvt_pk_bf16_f32 v8, v84, v85
	v_cvt_pk_bf16_f32 v9, v86, v87
	ds_read_b64_tr_b16 v[210:211], v218 offset:25600
	ds_read_b64_tr_b16 v[212:213], v218 offset:26112
	ds_read_b64_tr_b16 v[214:215], v218 offset:29696
	ds_read_b64_tr_b16 v[216:217], v218 offset:30208
	s_waitcnt lgkmcnt(4)
	v_mfma_f32_32x32x16_bf16 v[16:31], v[202:205], v[6:9], v[16:31]
	v_exp_f32_e32 v88, v88
	v_exp_f32_e32 v89, v89
	v_exp_f32_e32 v90, v90
	v_mfma_f32_32x32x16_bf16 v[32:47], v[206:209], v[6:9], v[32:47]
	v_exp_f32_e32 v91, v91
	v_exp_f32_e32 v92, v92
	v_exp_f32_e32 v93, v93
	v_mfma_f32_32x32x16_bf16 v[48:63], v[224:227], v[6:9], v[48:63]
	v_exp_f32_e32 v94, v94
	v_exp_f32_e32 v95, v95
	v_cvt_pk_bf16_f32 v10, v88, v89
	v_cvt_pk_bf16_f32 v11, v90, v91
	v_cvt_pk_bf16_f32 v12, v92, v93
	v_cvt_pk_bf16_f32 v13, v94, v95
	ds_read_b64_tr_b16 v[202:203], v218 offset:26624
	ds_read_b64_tr_b16 v[204:205], v218 offset:27136
	ds_read_b64_tr_b16 v[206:207], v218 offset:30720
	ds_read_b64_tr_b16 v[208:209], v218 offset:31232
	s_waitcnt lgkmcnt(4)
	v_mfma_f32_32x32x16_bf16 v[16:31], v[210:213], v[10:13], v[16:31]
	v_exp_f32_e32 v96, v96
	v_exp_f32_e32 v97, v97
	v_exp_f32_e32 v98, v98
	v_mfma_f32_32x32x16_bf16 v[32:47], v[214:217], v[10:13], v[32:47]
	v_exp_f32_e32 v99, v99
	v_exp_f32_e32 v100, v100
	v_exp_f32_e32 v101, v101
	v_mfma_f32_32x32x16_bf16 v[48:63], v[224:227], v[10:13], v[48:63]
	v_exp_f32_e32 v102, v102
	v_exp_f32_e32 v103, v103
	v_cvt_pk_bf16_f32 v228, v96, v97
	v_cvt_pk_bf16_f32 v229, v98, v99
	v_cvt_pk_bf16_f32 v230, v100, v101
	v_cvt_pk_bf16_f32 v231, v102, v103
	ds_read_b64_tr_b16 v[210:211], v218 offset:27648
	ds_read_b64_tr_b16 v[212:213], v218 offset:28160
	ds_read_b64_tr_b16 v[214:215], v218 offset:31744
	ds_read_b64_tr_b16 v[216:217], v218 offset:32256
	s_waitcnt lgkmcnt(4)
	v_mfma_f32_32x32x16_bf16 v[16:31], v[202:205], v[228:231], v[16:31]
	v_exp_f32_e32 v104, v104
	v_exp_f32_e32 v105, v105
	v_exp_f32_e32 v106, v106
	v_mfma_f32_32x32x16_bf16 v[32:47], v[206:209], v[228:231], v[32:47]
	v_exp_f32_e32 v107, v107
	v_exp_f32_e32 v108, v108
	v_exp_f32_e32 v109, v109
	v_mfma_f32_32x32x16_bf16 v[48:63], v[224:227], v[228:231], v[48:63]
	v_exp_f32_e32 v110, v110
	v_exp_f32_e32 v111, v111
	v_cvt_pk_bf16_f32 v232, v104, v105
	v_cvt_pk_bf16_f32 v233, v106, v107
	v_cvt_pk_bf16_f32 v234, v108, v109
	v_cvt_pk_bf16_f32 v235, v110, v111
	s_waitcnt lgkmcnt(0)
	s_nop 0
	v_mfma_f32_32x32x16_bf16 v[16:31], v[210:213], v[232:235], v[16:31]
	v_mfma_f32_32x32x16_bf16 v[32:47], v[214:217], v[232:235], v[32:47]
	v_mfma_f32_32x32x16_bf16 v[48:63], v[224:227], v[232:235], v[48:63]
